# priority toggling also in the scan-phase chunk loop (older wave raised for its MFMA part only)
# baseline (speedup 1.0000x reference)
.LBB0_203:
	s_setprio 1
	v_lshl_add_u64 v[32:33], s[0:1], 0, v[180:181]
	global_load_dword v205, v[32:33], off
	v_cvt_pk_bf16_f32 v32, v16, v17
	v_cvt_pk_bf16_f32 v33, v18, v19
	v_cvt_pk_bf16_f32 v34, v20, v21
	v_cvt_pk_bf16_f32 v35, v22, v23
	s_mov_b32 s4, 0xc020000
	s_waitcnt vmcnt(10)
	v_cndmask_b32_e64 v206, v119, v115, s[14:15]
	v_mfma_f32_32x32x16_bf16 v[48:63], v[96:99], v[32:35], 0
	v_cvt_pk_bf16_f32 v96, v24, v25
	v_cvt_pk_bf16_f32 v97, v26, v27
	v_cvt_pk_bf16_f32 v98, v28, v29
	v_cvt_pk_bf16_f32 v99, v30, v31
	v_cndmask_b32_e64 v207, v118, v114, s[14:15]
	v_cndmask_b32_e64 v208, v117, v113, s[14:15]
	v_cndmask_b32_e64 v209, v116, v112, s[14:15]
	v_mfma_f32_32x32x16_bf16 v[48:63], v[88:91], v[96:99], v[48:63]
	v_cvt_pk_bf16_f32 v88, v0, v1
	v_cvt_pk_bf16_f32 v89, v2, v3
	v_cvt_pk_bf16_f32 v90, v4, v5
	v_cvt_pk_bf16_f32 v91, v6, v7
	v_cndmask_b32_e64 v210, v209, v104, s[12:13]
	v_cndmask_b32_e64 v211, v208, v105, s[12:13]
	v_cndmask_b32_e64 v207, v207, v106, s[12:13]
	v_mfma_f32_32x32x16_bf16 v[32:47], v[100:103], v[32:35], 0
	v_cndmask_b32_e64 v206, v206, v107, s[12:13]
	v_cndmask_b32_e64 v209, v206, v111, s[10:11]
	v_cndmask_b32_e64 v208, v207, v110, s[10:11]
	v_cndmask_b32_e64 v207, v211, v109, s[10:11]
	v_cndmask_b32_e64 v206, v210, v108, s[10:11]
	v_add_u32_e32 v210, 0x1800, v204
	v_add_u32_e32 v211, 0x1c00, v204
	v_mfma_f32_32x32x16_bf16 v[48:63], v[80:83], v[88:91], v[48:63]
	v_cvt_pk_bf16_f32 v80, v8, v9
	v_cvt_pk_bf16_f32 v81, v10, v11
	v_cvt_pk_bf16_f32 v82, v12, v13
	v_cvt_pk_bf16_f32 v83, v14, v15
	s_mov_b64 s[6:7], 0x8000
	v_lshl_add_u64 v[180:181], v[180:181], 0, s[86:87]
	s_waitcnt vmcnt(2)
	v_mfma_f32_32x32x16_bf16 v[16:31], v[148:151], v[108:111], v[16:31]
	v_mfma_f32_32x32x16_bf16 v[0:15], v[132:135], v[108:111], v[0:15]
	v_mfma_f32_32x32x16_bf16 v[32:47], v[92:95], v[96:99], v[32:47]
	v_mfma_f32_32x32x16_bf16 v[16:31], v[144:147], v[104:107], v[16:31]
	v_mfma_f32_32x32x16_bf16 v[0:15], v[128:131], v[104:107], v[0:15]
	v_mfma_f32_32x32x16_bf16 v[32:47], v[84:87], v[88:91], v[32:47]
	v_mfma_f32_32x32x16_bf16 v[48:63], v[72:75], v[80:83], v[48:63]
	v_mfma_f32_32x32x16_bf16 v[16:31], v[140:143], v[112:115], v[16:31]
	v_mfma_f32_32x32x16_bf16 v[0:15], v[124:127], v[112:115], v[0:15]
	v_mfma_f32_32x32x16_bf16 v[32:47], v[76:79], v[80:83], v[32:47]
	v_lshl_add_u64 v[76:77], s[0:1], 0, v[194:195]
	v_add_co_u32_e32 v216, vcc, 0xe809000, v76
	s_mov_b32 s4, 0xc030000
	s_nop 0
	v_addc_co_u32_e32 v217, vcc, 0, v77, vcc
	v_mfma_f32_32x32x16_bf16 v[48:63], v[64:67], v[206:209], v[48:63]
	v_lshl_add_u64 v[64:65], s[0:1], 0, v[196:197]
	s_mov_b32 s4, 0xe009000
	global_load_dwordx4 v[96:99], v[216:217], off offset:-4096
	global_load_dwordx4 v[88:91], v[216:217], off offset:-3072
	global_load_dwordx4 v[80:83], v[216:217], off offset:-2048
	global_load_dwordx4 v[72:75], v[216:217], off offset:-1024
	global_load_dwordx4 v[100:103], v[216:217], off
	global_load_dwordx4 v[92:95], v[216:217], off offset:1024
	global_load_dwordx4 v[84:87], v[216:217], off offset:2048
	global_load_dwordx4 v[76:79], v[216:217], off offset:3072
	v_lshl_add_u64 v[192:193], v[192:193], 0, s[58:59]
	v_mfma_f32_32x32x16_bf16 v[16:31], v[136:139], v[116:119], v[16:31]
	v_lshl_add_u64 v[196:197], v[196:197], 0, s[6:7]
	v_mfma_f32_32x32x16_bf16 v[0:15], v[120:123], v[116:119], v[0:15]
	v_lshl_add_u64 v[116:117], s[0:1], 0, v[198:199]
	v_lshl_add_u64 v[198:199], v[198:199], 0, s[30:31]
	v_mfma_f32_32x32x16_bf16 v[32:47], v[68:71], v[206:209], v[32:47]
	s_getreg_b32 s39, hwreg(HW_REG_HW_ID, 0, 4)
	s_bitcmp1_b32 s39, 0
	s_cbranch_scc1 .Lgp200
	s_setprio 0
.Lgp200:
	v_add_co_u32_e32 v68, vcc, s4, v64
	s_and_b32 s4, s5, 0x100
	s_nop 0
	v_addc_co_u32_e32 v69, vcc, 0, v65, vcc
	v_lshl_add_u32 v206, s4, 2, v202
	global_load_dwordx4 v[64:67], v[68:69], off offset:-4096
	s_nop 0
	global_load_dwordx4 v[68:71], v[68:69], off
	ds_read_b128 v[136:139], v206 offset:32768
	ds_read_b128 v[140:143], v206 offset:32800
	ds_read_b128 v[104:107], v206 offset:32896
	s_mov_b32 s4, 0xd080000
	s_addk_i32 s5, 0x100
	s_waitcnt lgkmcnt(2)
	v_pk_mul_f32 v[16:17], v[16:17], v[136:137]
	v_pk_mul_f32 v[18:19], v[18:19], v[138:139]
	ds_read_b128 v[136:139], v206 offset:32832
	s_waitcnt lgkmcnt(1)
	v_pk_mul_f32 v[0:1], v[0:1], v[104:105]
	v_pk_mul_f32 v[2:3], v[2:3], v[106:107]
	ds_read_b128 v[104:107], v206 offset:32928
	v_pk_mul_f32 v[20:21], v[20:21], v[140:141]
	s_waitcnt lgkmcnt(1)
	v_pk_mul_f32 v[24:25], v[24:25], v[136:137]
	v_pk_mul_f32 v[26:27], v[26:27], v[138:139]
	ds_read_b128 v[136:139], v206 offset:32864
	s_waitcnt lgkmcnt(1)
	v_pk_mul_f32 v[4:5], v[4:5], v[104:105]
	v_pk_mul_f32 v[6:7], v[6:7], v[106:107]
	ds_read_b128 v[104:107], v206 offset:32960
	v_pk_mul_f32 v[22:23], v[22:23], v[142:143]
	s_waitcnt lgkmcnt(1)
	v_pk_mul_f32 v[28:29], v[28:29], v[136:137]
	v_lshl_add_u64 v[136:137], s[0:1], 0, v[194:195]
	v_add_co_u32_e32 v212, vcc, 0xd009000, v136
	s_waitcnt lgkmcnt(0)
	v_pk_mul_f32 v[8:9], v[8:9], v[104:105]
	v_pk_mul_f32 v[10:11], v[10:11], v[106:107]
	ds_read_b128 v[104:107], v206 offset:32992
	v_addc_co_u32_e32 v213, vcc, 0, v137, vcc
	v_pk_mul_f32 v[30:31], v[30:31], v[138:139]
	s_nop 0
	s_waitcnt lgkmcnt(0)
	v_pk_mul_f32 v[12:13], v[12:13], v[104:105]
	v_pk_mul_f32 v[14:15], v[14:15], v[106:107]
	global_load_dwordx4 v[108:111], v[116:117], off
	global_load_dwordx4 v[104:107], v[116:117], off offset:1024
	global_load_dwordx4 v[112:115], v[116:117], off offset:2048
	s_nop 0
	global_load_dwordx4 v[116:119], v[116:117], off offset:3072
	s_nop 0
	global_load_dwordx4 v[120:123], v[212:213], off offset:3072
	global_load_dwordx4 v[124:127], v[212:213], off offset:2048
	global_load_dwordx4 v[128:131], v[212:213], off offset:1024
	global_load_dwordx4 v[132:135], v[212:213], off
	global_load_dwordx4 v[136:139], v[212:213], off offset:-1024
	global_load_dwordx4 v[140:143], v[212:213], off offset:-2048
	global_load_dwordx4 v[144:147], v[212:213], off offset:-3072
	global_load_dwordx4 v[148:151], v[212:213], off offset:-4096
	s_and_b32 s4, s5, 0x100
	v_lshl_add_u32 v206, s4, 2, v155
	s_waitcnt vmcnt(22)
	ds_write_b32 v206, v205 offset:32768
	ds_write2_b32 v204, v48, v49 offset1:32
	ds_write2_b32 v204, v50, v51 offset0:64 offset1:96
	v_add_u32_e32 v205, 0x400, v204
	v_add_u32_e32 v206, 0x800, v204
	v_add_u32_e32 v207, 0xc00, v204
	v_add_u32_e32 v208, 0x1000, v204
	v_add_u32_e32 v209, 0x1400, v204
	ds_write2_b32 v205, v52, v53 offset1:32
	ds_write2_b32 v205, v54, v55 offset0:64 offset1:96
	ds_write2_b32 v206, v56, v57 offset1:32
	ds_write2_b32 v206, v58, v59 offset0:64 offset1:96
	ds_write2_b32 v207, v60, v61 offset1:32
	ds_write2_b32 v207, v62, v63 offset0:64 offset1:96
	ds_write2_b32 v208, v32, v33 offset1:32
	ds_write2_b32 v208, v34, v35 offset0:64 offset1:96
	ds_write2_b32 v209, v36, v37 offset1:32
	ds_write2_b32 v209, v38, v39 offset0:64 offset1:96
	ds_write2_b32 v210, v40, v41 offset1:32
	ds_write2_b32 v210, v42, v43 offset0:64 offset1:96
	ds_write2_b32 v211, v44, v45 offset1:32
	ds_write2_b32 v211, v46, v47 offset0:64 offset1:96
	s_waitcnt lgkmcnt(0)
	s_barrier
	ds_read_b128 v[32:35], v203
	ds_read_b128 v[36:39], v203 offset:16
	ds_read_b128 v[40:43], v203 offset:8192
	ds_read_b128 v[44:47], v203 offset:16384
	ds_read_b128 v[48:51], v203 offset:24576
	v_lshl_add_u64 v[194:195], v[194:195], 0, s[6:7]
	s_cmpk_eq_i32 s5, 0xf00
	s_waitcnt lgkmcnt(2)
	v_pk_add_f32 v[32:33], v[32:33], v[40:41]
	s_waitcnt lgkmcnt(1)
	v_pk_add_f32 v[32:33], v[32:33], v[44:45]
	s_waitcnt lgkmcnt(0)
	v_pk_add_f32 v[48:49], v[32:33], v[48:49]
	v_pk_add_f32 v[32:33], v[34:35], v[42:43]
	ds_read_b128 v[40:43], v203 offset:16400
	v_pk_add_f32 v[32:33], v[32:33], v[46:47]
	ds_read_b128 v[44:47], v203 offset:24592
	v_pk_add_f32 v[50:51], v[32:33], v[50:51]
	ds_read_b128 v[32:35], v203 offset:8208
	s_waitcnt lgkmcnt(0)
	v_pk_add_f32 v[32:33], v[36:37], v[32:33]
	s_nop 0
	v_pk_add_f32 v[32:33], v[32:33], v[40:41]
	s_nop 0
	v_pk_add_f32 v[36:37], v[32:33], v[44:45]
	v_pk_add_f32 v[32:33], v[38:39], v[34:35]
	v_cvt_pk_bf16_f32 v34, v36, v37
	v_pk_add_f32 v[32:33], v[32:33], v[42:43]
	v_lshl_add_u64 v[36:37], s[0:1], 0, v[182:183]
	v_pk_add_f32 v[38:39], v[32:33], v[46:47]
	v_cvt_pk_bf16_f32 v32, v48, v49
	v_cvt_pk_bf16_f32 v33, v50, v51
	v_cvt_pk_bf16_f32 v35, v38, v39
	v_lshl_add_u64 v[182:183], v[182:183], 0, s[90:91]
	global_store_dwordx4 v[36:37], v[32:35], off offset:-8
	s_barrier
	s_cbranch_scc0 .LBB0_203
	v_cvt_pk_bf16_f32 v16, v16, v17
	v_cvt_pk_bf16_f32 v17, v18, v19
	v_cvt_pk_bf16_f32 v18, v20, v21
	v_cvt_pk_bf16_f32 v19, v22, v23
	v_cvt_pk_bf16_f32 v0, v0, v1
	v_cvt_pk_bf16_f32 v1, v2, v3
	s_waitcnt vmcnt(22)
	v_mfma_f32_32x32x16_bf16 v[48:63], v[96:99], v[16:19], 0
	v_cvt_pk_bf16_f32 v2, v4, v5
	v_cvt_pk_bf16_f32 v3, v6, v7
	v_cvt_pk_bf16_f32 v4, v8, v9
	v_cvt_pk_bf16_f32 v5, v10, v11
	v_cvt_pk_bf16_f32 v6, v12, v13
	v_cvt_pk_bf16_f32 v7, v14, v15
	s_lshl_b32 s66, s66, 1
	s_waitcnt vmcnt(18)
	v_mfma_f32_32x32x16_bf16 v[32:47], v[100:103], v[16:19], 0
	v_cvt_pk_bf16_f32 v16, v24, v25
	v_cvt_pk_bf16_f32 v17, v26, v27
	v_cvt_pk_bf16_f32 v18, v28, v29
	v_cvt_pk_bf16_f32 v19, v30, v31
	s_add_i32 s23, s23, s64
	s_add_i32 s22, s22, s64
	v_mfma_f32_32x32x16_bf16 v[48:63], v[88:91], v[16:19], v[48:63]
	s_waitcnt vmcnt(17)
	v_mfma_f32_32x32x16_bf16 v[32:47], v[92:95], v[16:19], v[32:47]
	v_mfma_f32_32x32x16_bf16 v[48:63], v[80:83], v[0:3], v[48:63]
	s_waitcnt vmcnt(16)
	v_mfma_f32_32x32x16_bf16 v[32:47], v[84:87], v[0:3], v[32:47]
	s_waitcnt vmcnt(9)
	v_cndmask_b32_e64 v0, v119, v115, s[14:15]
	v_cndmask_b32_e64 v1, v118, v114, s[14:15]
	v_cndmask_b32_e64 v2, v117, v113, s[14:15]
	v_cndmask_b32_e64 v3, v116, v112, s[14:15]
	v_cndmask_b32_e64 v8, v3, v104, s[12:13]
	v_cndmask_b32_e64 v9, v2, v105, s[12:13]
	v_cndmask_b32_e64 v1, v1, v106, s[12:13]
	v_mfma_f32_32x32x16_bf16 v[48:63], v[72:75], v[4:7], v[48:63]
	v_cndmask_b32_e64 v0, v0, v107, s[12:13]
	v_cndmask_b32_e64 v3, v0, v111, s[10:11]
	v_cndmask_b32_e64 v2, v1, v110, s[10:11]
	v_cndmask_b32_e64 v1, v9, v109, s[10:11]
	v_cndmask_b32_e64 v0, v8, v108, s[10:11]
	v_lshl_add_u64 v[8:9], v[164:165], 0, s[66:67]
	s_lshl_b32 s66, s24, 1
	v_mfma_f32_32x32x16_bf16 v[32:47], v[76:79], v[4:7], v[32:47]
	v_lshl_add_u64 v[8:9], v[8:9], 0, s[66:67]
	v_lshl_add_u64 v[8:9], v[8:9], 0, v[186:187]
	s_cmpk_gt_i32 s23, 0x1ff
	v_mfma_f32_32x32x16_bf16 v[48:63], v[64:67], v[0:3], v[48:63]
	v_lshl_add_u64 v[64:65], v[8:9], 0, s[2:3]
	ds_write_b32 v155, v187 offset:32768
	s_nop 9
	ds_write2_b32 v204, v48, v49 offset1:32
	v_mfma_f32_32x32x16_bf16 v[32:47], v[68:71], v[0:3], v[32:47]
	ds_write2_b32 v204, v50, v51 offset0:64 offset1:96
	ds_write2_b32 v205, v52, v53 offset1:32
	ds_write2_b32 v205, v54, v55 offset0:64 offset1:96
	ds_write2_b32 v206, v56, v57 offset1:32
	ds_write2_b32 v206, v58, v59 offset0:64 offset1:96
	ds_write2_b32 v207, v60, v61 offset1:32
	ds_write2_b32 v207, v62, v63 offset0:64 offset1:96
	s_nop 4
	ds_write2_b32 v208, v32, v33 offset1:32
	ds_write2_b32 v208, v34, v35 offset0:64 offset1:96
	ds_write2_b32 v209, v36, v37 offset1:32
	ds_write2_b32 v209, v38, v39 offset0:64 offset1:96
	ds_write2_b32 v210, v40, v41 offset1:32
	ds_write2_b32 v210, v42, v43 offset0:64 offset1:96
	ds_write2_b32 v211, v44, v45 offset1:32
	ds_write2_b32 v211, v46, v47 offset0:64 offset1:96
	s_waitcnt lgkmcnt(0)
	s_barrier
	ds_read_b128 v[0:3], v203 offset:8192
	ds_read_b128 v[4:7], v203
	ds_read_b128 v[8:11], v203 offset:16
	ds_read_b128 v[12:15], v203 offset:16384
	ds_read_b128 v[16:19], v203 offset:24576
	ds_read_b128 v[20:23], v203 offset:8208
	ds_read_b128 v[24:27], v203 offset:16400
	ds_read_b128 v[28:31], v203 offset:24592
	s_waitcnt lgkmcnt(6)
	v_pk_add_f32 v[0:1], v[4:5], v[0:1]
	v_pk_add_f32 v[2:3], v[6:7], v[2:3]
	s_waitcnt lgkmcnt(2)
	v_pk_add_f32 v[4:5], v[8:9], v[20:21]
	v_pk_add_f32 v[0:1], v[0:1], v[12:13]
	v_pk_add_f32 v[2:3], v[2:3], v[14:15]
	s_waitcnt lgkmcnt(1)
	v_pk_add_f32 v[4:5], v[4:5], v[24:25]
	v_pk_add_f32 v[6:7], v[10:11], v[22:23]
	v_pk_add_f32 v[0:1], v[0:1], v[16:17]
	v_pk_add_f32 v[2:3], v[2:3], v[18:19]
	s_waitcnt lgkmcnt(0)
	v_pk_add_f32 v[4:5], v[4:5], v[28:29]
	v_pk_add_f32 v[6:7], v[6:7], v[26:27]
	v_cvt_pk_bf16_f32 v0, v0, v1
	v_pk_add_f32 v[6:7], v[6:7], v[30:31]
	v_cvt_pk_bf16_f32 v1, v2, v3
	v_cvt_pk_bf16_f32 v2, v4, v5
	v_add_co_u32_e32 v4, vcc, 0x3c0000, v64
	v_cvt_pk_bf16_f32 v3, v6, v7
	s_nop 0
	v_addc_co_u32_e32 v5, vcc, 0, v65, vcc
	global_store_dwordx4 v[4:5], v[0:3], off
	s_barrier
	s_cbranch_scc0 .LBB0_198
